# attention main loop: V tiles also by LDS-DMA (lane-linear 1-KB blocks of the transposed-read image; issued at the start of the next half-step, exit path issues the pending one), no V staging registers
# speedup vs baseline: 1.0208x; 1.0076x over previous
; #define SBAR() __builtin_amdgcn_sched_barrier(0)
; __device__ __forceinline__ int v_st(int k, int c) { const int kk = (k & ~0xC) | ((k & 4) << 1) | ((k & 8) >> 1); return ((kk >> 3) * 4 + (c >> 5)) * 512 + ((kk & 7) * 32 + (c & 31)) * 2; }
; __device__ __forceinline__ int v_rd_base(int lane) { return ((lane & 3) << 3) | (((lane >> 2) & 3) << 6) | (((lane >> 4) & 1) << 5) | (((lane >> 5) & 1) << 8); }
; #define VMW() asm volatile("s_waitcnt vmcnt(0)" ::: "memory")
; #define SLOAD_H(Kp, Vp, k0) do { S.st_v0 = load8(ROW(Vp, k0, sr)); S.st_v1 = load8(ROW(Vp, k0, 32 + sr));              \
;                          S.st_k0 = load8(ROW(Kp, k0, sr)); S.st_k1 = load8(ROW(Kp, k0, 32 + sr)); } while (0)
; #define SWRITE_HV(bf) do { *(bf16x8*)(V_lds + (bf) * SHM_V + vst0) = S.st_v0; *(bf16x8*)(V_lds + (bf) * SHM_V + vst1) = S.st_v1; } while (0)
; #define SWRITE_H(bf) do { SWRITE_HV(bf); SWRITE_HK(bf); } while (0)
; #define MASKT(P0_, P1_, t) do { const int kb_ = KBASE(t); if (kb_ + KVBLK - 1 > qlo) mask_tile(P0_, P1_, qm - kb_, (unsigned)W); } while (0)
; __device__ __forceinline__ void moba_block(const BlockRef& cur, const BlockRef& nxt, char* lds, Seam& S) {
;     ...
;     const int qlo = cur.P0 + wid * QBLK, qm = qlo + r32 - 4 * hi;
;     char* V_lds = lds; char* K_lds = lds + 2 * SHM_V;
;     float* ws = (float*)(lds + 2 * SHM_V + 2 * SHM_K) + wid * 64; float* li_l = ws, * al_l = ws + 32;
;     float m_reg = -1e30f, l_reg = 0; f32x16 o[4] = {};
;     const int sr = tid >> 4, sc = (tid & 15) * 8, vst0 = v_st(sr, sc), vst1 = v_st(32 + sr, sc), kws = KSWZ(sr, sc * 2);
;     const int vb0 = (int)(uintptr_t)V_lds + v_rd_base(lane);
;     const bf16* Kh = cur.K; const bf16* Vh = cur.V;
;     const int qb = cur.qb;
;     const unsigned sel = gate_select(S.qr, lds, qb, r32, hi);
;     ...
;     constexpr int NQL = 8;
;     ...
;     f32x16 pA0, pA1, pB0, pB1; float mnA, mnB, alA, alB; bf16x8 pa0, pa1, pa2, pa3;
;     SWRITE_HV(0); SBAR();
;     if (NT > 1) { SLOAD_H(Kh, Vh, KBASE(1)); }
;     SBAR(); qkt<0>(pA0, pA1, K_lds, r32, hi, S.qr);
;     MASKT(pA0, pA1, 0); partialSM(pA0, pA1, m_reg, mnA, alA, RSEL(0));
;     if (NT > 1) { VMW(); SWRITE_H(1); }
;     __syncthreads();
.LBB0_88:
	s_and_b32 s0, s3, 0x3fffffc0
	v_and_b32_e32 v51, 63, v183
	s_lshl_b32 s0, s0, 2
	s_lshl_b32 s2, s44, 2
	s_add_i32 s0, s0, 0
	v_lshlrev_b32_e32 v52, 8, v166
	v_and_b32_e32 v53, 0x70, v183
	v_lshlrev_b32_e32 v54, 4, v51
	s_xor_b64 s[10:11], s[10:11], -1
	s_add_i32 s2, s2, 4
	s_add_i32 s7, s0, 0x10000
	v_bitop3_b32 v53, v98, v52, v53 bitop3:0xde
	v_lshlrev_b32_e32 v52, 3, v51
	v_and_b32_e32 v54, 0xc0, v54
	v_lshlrev_b32_e32 v55, 1, v51
	v_and_or_b32 v54, v52, 24, v54
	v_and_b32_e32 v55, 32, v55
	v_and_b32_e32 v52, 0x100, v52
	s_cmp_lg_u32 0, -1
	v_or3_b32 v52, v54, v55, v52
	s_cselect_b32 s0, 0, 0
	v_add_u32_e32 v185, s0, v52
	v_and_b32_e32 v52, 1, v165
	v_cmp_eq_u32_e32 vcc, 1, v52
	v_max_f32_e32 v52, v19, v19
	v_max_f32_e32 v54, v18, v18
	v_max_f32_e32 v52, v54, v52
	v_max3_f32 v52, v52, v20, v21
	v_max3_f32 v52, v52, v22, v23
	v_max3_f32 v52, v52, v24, v25
	v_max3_f32 v52, v52, v26, v27
	v_max3_f32 v52, v52, v28, v29
	v_max3_f32 v52, v52, v30, v31
	v_max3_f32 v52, v52, v32, v33
	v_max3_f32 v52, v52, v2, v3
	v_max3_f32 v52, v52, v4, v5
	v_max3_f32 v52, v52, v6, v7
	v_max3_f32 v52, v52, v8, v9
	v_max3_f32 v52, v52, v10, v11
	s_cmp_lt_i32 s44, 1
	v_max3_f32 v52, v52, v12, v13
	s_cselect_b64 s[0:1], -1, 0
	v_max3_f32 v52, v52, v14, v15
	v_max3_f32 v52, v52, v16, v17
	s_or_b64 vcc, s[0:1], vcc
	v_cndmask_b32_e32 v52, v220, v52, vcc
	v_mov_b32_e32 v54, v52
	s_nop 1
	v_permlane32_swap_b32_e32 v52, v54
	v_max_f32_e32 v54, v54, v54
	v_max_f32_e32 v52, v52, v52
	v_max_f32_e32 v52, v52, v54
	v_add_f32_e32 v54, 0x7149f2ca, v52
	v_mul_f32_e32 v54, 0x3db504f3, v54
	v_max_f32_e32 v52, 0xf149f2ca, v52
	v_cmp_ge_f32_e64 s[38:39], s91, v54
	v_sub_f32_e32 v54, 0xf149f2ca, v52
	v_mul_f32_e32 v54, 0x3e0293ee, v54
	s_cmp_eq_u64 s[38:39], exec
	v_exp_f32_e32 v54, v54
	s_cselect_b64 s[38:39], -1, 0
	v_mov_b32_e32 v55, 0xf149f2ca
	v_cndmask_b32_e64 v198, v52, v55, s[38:39]
	v_mul_f32_e32 v52, 0xbe0293ee, v198
	v_cndmask_b32_e32 v52, v220, v52, vcc
	v_cndmask_b32_e64 v196, v54, 1.0, s[38:39]
	v_mov_b32_e32 v54, v52
	v_fmamk_f32 v18, v18, 0x3e0293ee, v52
	v_fmamk_f32 v19, v19, 0x3e0293ee, v52
	v_fmamk_f32 v20, v20, 0x3e0293ee, v52
	v_fmamk_f32 v21, v21, 0x3e0293ee, v52
	v_fmamk_f32 v22, v22, 0x3e0293ee, v52
	v_fmamk_f32 v23, v23, 0x3e0293ee, v52
	v_fmamk_f32 v24, v24, 0x3e0293ee, v52
	v_fmamk_f32 v25, v25, 0x3e0293ee, v52
	v_fmamk_f32 v26, v26, 0x3e0293ee, v52
	v_fmamk_f32 v27, v27, 0x3e0293ee, v52
	v_fmamk_f32 v28, v28, 0x3e0293ee, v52
	v_fmamk_f32 v29, v29, 0x3e0293ee, v52
	v_fmamk_f32 v30, v30, 0x3e0293ee, v52
	v_fmamk_f32 v31, v31, 0x3e0293ee, v52
	v_fmamk_f32 v32, v32, 0x3e0293ee, v52
	v_fmac_f32_e32 v54, 0x3e0293ee, v33
	s_add_i32 s0, s6, 0xbfffff45
	v_pk_fma_f32 v[178:179], v[2:3], s[20:21], v[52:53] op_sel_hi:[1,0,0]
	v_exp_f32_e32 v231, v18
	v_exp_f32_e32 v233, v19
	v_exp_f32_e32 v229, v20
	v_exp_f32_e32 v232, v21
	v_exp_f32_e32 v228, v22
	v_exp_f32_e32 v230, v23
	v_exp_f32_e32 v226, v24
	v_exp_f32_e32 v227, v25
	v_exp_f32_e32 v223, v26
	v_exp_f32_e32 v225, v27
	v_exp_f32_e32 v209, v28
	v_exp_f32_e32 v224, v29
	v_exp_f32_e32 v206, v30
	v_exp_f32_e32 v208, v31
	v_exp_f32_e32 v205, v32
	v_exp_f32_e32 v207, v54
	v_add_u32_e32 v2, s0, v184
	s_waitcnt vmcnt(0)
	v_add_u32_e32 v188, 0, v53
	v_cmp_gt_u32_e64 s[38:39], 32, v51
	v_lshl_add_u32 v186, v50, 2, s7
	v_sub_u32_e32 v197, v2, v50
	v_mov_b32_e32 v50, v99
	v_mov_b32_e32 v51, v99
	v_pk_fma_f32 v[154:155], v[16:17], s[20:21], v[52:53] op_sel_hi:[1,0,0]
	v_pk_fma_f32 v[160:161], v[14:15], s[20:21], v[52:53] op_sel_hi:[1,0,0]
	v_pk_fma_f32 v[180:181], v[12:13], s[20:21], v[52:53] op_sel_hi:[1,0,0]
	v_pk_fma_f32 v[152:153], v[10:11], s[20:21], v[52:53] op_sel_hi:[1,0,0]
	v_pk_fma_f32 v[156:157], v[8:9], s[20:21], v[52:53] op_sel_hi:[1,0,0]
	v_pk_fma_f32 v[158:159], v[6:7], s[20:21], v[52:53] op_sel_hi:[1,0,0]
	v_pk_fma_f32 v[162:163], v[4:5], s[20:21], v[52:53] op_sel_hi:[1,0,0]
	s_waitcnt vmcnt(3)
	ds_write_b128 v191, v[34:37] offset:16384
	s_waitcnt vmcnt(2)
	ds_write_b128 v192, v[38:41] offset:16384
	s_waitcnt vmcnt(1)
	ds_write_b128 v188, v[42:45] offset:49152
	s_waitcnt vmcnt(0)
	ds_write_b128 v188, v[46:49] offset:57344
	v_mov_b32_e32 v52, v99
	v_mov_b32_e32 v53, v99
	v_mov_b32_e32 v54, v99
	v_mov_b32_e32 v55, v99
	v_mov_b32_e32 v56, v99
	v_mov_b32_e32 v57, v99
	v_mov_b32_e32 v58, v99
	v_mov_b32_e32 v59, v99
	v_mov_b32_e32 v60, v99
	v_mov_b32_e32 v61, v99
	v_mov_b32_e32 v62, v99
	v_mov_b32_e32 v63, v99
	v_mov_b32_e32 v64, v99
	v_mov_b32_e32 v65, v99
	v_mov_b64_e32 v[34:35], v[50:51]
	v_mov_b64_e32 v[18:19], v[50:51]
	v_mov_b64_e32 v[2:3], v[50:51]
	s_mov_b32 s3, 3
	v_lshl_add_u64 v[170:171], s[22:23], 0, v[98:99]
	v_lshl_add_u64 v[176:177], s[30:31], 0, v[98:99]
	v_lshl_add_u32 v187, v184, 2, s7
	v_mov_b32_e32 v189, 0
	s_movk_i32 s7, 0x7f
	v_mov_b64_e32 v[36:37], v[52:53]
	v_mov_b64_e32 v[38:39], v[54:55]
	v_mov_b64_e32 v[40:41], v[56:57]
	v_mov_b64_e32 v[42:43], v[58:59]
	v_mov_b64_e32 v[44:45], v[60:61]
	v_mov_b64_e32 v[46:47], v[62:63]
	v_mov_b64_e32 v[48:49], v[64:65]
	v_mov_b64_e32 v[20:21], v[52:53]
	v_mov_b64_e32 v[22:23], v[54:55]
	v_mov_b64_e32 v[24:25], v[56:57]
	v_mov_b64_e32 v[26:27], v[58:59]
	v_mov_b64_e32 v[28:29], v[60:61]
	v_mov_b64_e32 v[30:31], v[62:63]
	v_mov_b64_e32 v[32:33], v[64:65]
	v_mov_b64_e32 v[4:5], v[52:53]
	v_mov_b64_e32 v[6:7], v[54:55]
	v_mov_b64_e32 v[8:9], v[56:57]
	v_mov_b64_e32 v[10:11], v[58:59]
	v_mov_b64_e32 v[12:13], v[60:61]
	v_mov_b64_e32 v[14:15], v[62:63]
	v_mov_b64_e32 v[16:17], v[64:65]
	s_mov_b32 s100, 0
	v_readfirstlane_b32 s32, v0
	s_lshr_b32 s32, s32, 6
	s_lshl_b32 s32, s32, 10
	s_add_i32 s32, s32, 0x8000
	v_lshrrev_b32_e32 v236, 4, v0
	v_and_b32_e32 v236, 7, v236
	v_and_b32_e32 v237, 15, v0
	v_xor_b32_e32 v236, v236, v237
	v_sub_u32_e32 v236, v236, v237
	v_lshlrev_b32_e32 v236, 4, v236
	v_ashrrev_i32_e32 v237, 31, v236
	v_lshl_add_u64 v[234:235], v[176:177], 0, v[236:237]
	v_lshrrev_b32_e32 v240, 6, v0
	v_bfe_u32 v241, v0, 2, 3
	v_lshrrev_b32_e32 v250, 1, v240
	v_lshlrev_b32_e32 v250, 4, v250
	v_and_b32_e32 v251, 4, v241
	v_lshl_or_b32 v250, v251, 1, v250
	v_and_b32_e32 v251, 1, v240
	v_lshl_or_b32 v250, v251, 2, v250
	v_and_b32_e32 v251, 3, v241
	v_or_b32_e32 v250, v250, v251
	v_lshlrev_b32_e32 v250, 8, v250
	v_bfe_u32 v251, v0, 5, 1
	v_lshl_or_b32 v250, v251, 6, v250
	v_and_b32_e32 v251, 3, v0
	v_lshl_or_b32 v250, v251, 4, v250
	v_lshrrev_b32_e32 v251, 4, v0
	v_lshlrev_b32_e32 v251, 8, v251
	v_and_b32_e32 v240, 15, v0
	v_lshl_or_b32 v251, v240, 4, v251
	v_sub_u32_e32 v240, v250, v251
	v_ashrrev_i32_e32 v241, 31, v240
	v_lshl_add_u64 v[238:239], v[170:171], 0, v[240:241]
	s_waitcnt lgkmcnt(0)
	s_barrier
.LBB0_89:
	s_waitcnt vmcnt(0)
	s_cmp_eq_u32 s100, 0
	s_cbranch_scc1 .Lmy_hs1_nov
	s_lshl_b32 m0, s32, 1
	s_sub_i32 m0, m0, 0xc000
	s_nop 0
	global_load_lds_dwordx4 v[242:243], off
	s_add_i32 m0, m0, 896
	s_nop 0
	global_load_lds_dwordx4 v[242:243], off offset:128
.Lmy_hs1_nov:
	s_mov_b32 s100, 0
	ds_read_b128 v[66:69], v169 offset:49152
	ds_read_b128 v[70:73], v169 offset:57344
	ds_read_b128 v[100:103], v193 offset:49152
	ds_read_b128 v[136:139], v193 offset:57344
	v_add_f32_e32 v148, 0, v231
	v_add_f32_e32 v148, v233, v148
	v_add_f32_e32 v148, v229, v148
	v_add_f32_e32 v148, v232, v148
	v_add_f32_e32 v148, v228, v148
	v_add_f32_e32 v148, v230, v148
	v_add_f32_e32 v148, v226, v148
	v_add_f32_e32 v148, v227, v148
	v_add_f32_e32 v148, v223, v148
	v_add_f32_e32 v148, v225, v148
	v_add_f32_e32 v148, v209, v148
	v_add_f32_e32 v148, v224, v148
	v_add_f32_e32 v148, v206, v148
	v_add_f32_e32 v148, v208, v148
	v_add_f32_e32 v148, v205, v148
	v_add_f32_e32 v148, v207, v148
	v_exp_f32_e32 v140, v152
	v_exp_f32_e32 v141, v153
	v_exp_f32_e32 v142, v180
	v_exp_f32_e32 v143, v181
	s_waitcnt lgkmcnt(3)
	v_mfma_f32_32x32x16_bf16 v[82:97], v[66:69], v[132:135], 0
	v_exp_f32_e32 v144, v160
	v_exp_f32_e32 v145, v161
	v_exp_f32_e32 v146, v154
	v_exp_f32_e32 v147, v155
	s_waitcnt lgkmcnt(2)
	v_mfma_f32_32x32x16_bf16 v[66:81], v[70:73], v[132:135], 0
	v_exp_f32_e32 v178, v178
	v_exp_f32_e32 v179, v179
	v_exp_f32_e32 v162, v162
	v_exp_f32_e32 v163, v163
	s_waitcnt lgkmcnt(1)
	v_mfma_f32_32x32x16_bf16 v[82:97], v[100:103], v[128:131], v[82:97]
	v_add_f32_e32 v148, v178, v148
	v_add_f32_e32 v148, v179, v148
	v_add_f32_e32 v148, v162, v148
	v_exp_f32_e32 v158, v158
	s_waitcnt lgkmcnt(0)
	v_mfma_f32_32x32x16_bf16 v[66:81], v[136:139], v[128:131], v[66:81]
	v_exp_f32_e32 v159, v159
	v_exp_f32_e32 v156, v156
	v_exp_f32_e32 v157, v157
	v_add_f32_e32 v148, v163, v148
	ds_read_b128 v[100:103], v194 offset:49152
	ds_read_b128 v[136:139], v194 offset:57344
	s_waitcnt lgkmcnt(1)
	v_mfma_f32_32x32x16_bf16 v[82:97], v[100:103], v[124:127], v[82:97]
	v_add_f32_e32 v148, v158, v148
	v_add_f32_e32 v148, v159, v148
	v_add_f32_e32 v148, v156, v148
	v_add_f32_e32 v148, v157, v148
	s_waitcnt lgkmcnt(0)
	v_mfma_f32_32x32x16_bf16 v[66:81], v[136:139], v[124:127], v[66:81]
	v_add_f32_e32 v148, v140, v148
	v_add_f32_e32 v148, v141, v148
	v_add_f32_e32 v148, v142, v148
	v_add_f32_e32 v148, v143, v148
	ds_read_b128 v[100:103], v195 offset:49152
	ds_read_b128 v[136:139], v195 offset:57344
	s_waitcnt lgkmcnt(1)
	v_mfma_f32_32x32x16_bf16 v[82:97], v[100:103], v[120:123], v[82:97]
	v_add_f32_e32 v148, v144, v148
	v_add_f32_e32 v148, v145, v148
	v_add_f32_e32 v148, v146, v148
	v_add_f32_e32 v199, v147, v148
	s_waitcnt lgkmcnt(0)
	v_mfma_f32_32x32x16_bf16 v[66:81], v[136:139], v[120:123], v[66:81]
	v_mov_b32_e32 v200, v199
	s_nop 1
	v_permlane32_swap_b32_e32 v199, v200
	v_cvt_pk_bf16_f32 v148, v231, v233
	v_cvt_pk_bf16_f32 v149, v229, v232
	v_cvt_pk_bf16_f32 v150, v228, v230
	ds_read_b128 v[100:103], v169 offset:49280
	ds_read_b128 v[136:139], v169 offset:57472
	s_waitcnt lgkmcnt(1)
	v_mfma_f32_32x32x16_bf16 v[82:97], v[100:103], v[116:119], v[82:97]
	v_cvt_pk_bf16_f32 v151, v226, v227
	v_cvt_pk_bf16_f32 v152, v223, v225
	v_cvt_pk_bf16_f32 v153, v209, v224
	s_waitcnt lgkmcnt(0)
	v_mfma_f32_32x32x16_bf16 v[66:81], v[136:139], v[116:119], v[66:81]
	v_cvt_pk_bf16_f32 v154, v206, v208
	v_cvt_pk_bf16_f32 v155, v205, v207
	v_cvt_pk_bf16_f32 v158, v158, v159
	ds_read_b128 v[100:103], v193 offset:49280
	ds_read_b128 v[136:139], v193 offset:57472
	s_waitcnt lgkmcnt(1)
	v_mfma_f32_32x32x16_bf16 v[82:97], v[100:103], v[112:115], v[82:97]
	v_cvt_pk_bf16_f32 v159, v156, v157
	v_cvt_pk_bf16_f32 v156, v178, v179
	v_cvt_pk_bf16_f32 v157, v162, v163
	s_waitcnt lgkmcnt(0)
	v_mfma_f32_32x32x16_bf16 v[66:81], v[136:139], v[112:115], v[66:81]
	v_cvt_pk_bf16_f32 v160, v140, v141
	v_cvt_pk_bf16_f32 v161, v142, v143
	v_cvt_pk_bf16_f32 v162, v144, v145
	ds_read_b128 v[100:103], v194 offset:49280
	ds_read_b128 v[136:139], v194 offset:57472
	s_waitcnt lgkmcnt(1)
	v_mfma_f32_32x32x16_bf16 v[82:97], v[100:103], v[108:111], v[82:97]
	v_cvt_pk_bf16_f32 v163, v146, v147
	s_nop 0
	v_permlane32_swap_b32_e32 v148, v150
	v_permlane32_swap_b32_e32 v149, v151
	s_waitcnt lgkmcnt(0)
	v_mfma_f32_32x32x16_bf16 v[66:81], v[136:139], v[108:111], v[66:81]
	v_permlane32_swap_b32_e32 v152, v154
	v_permlane32_swap_b32_e32 v153, v155
	v_permlane32_swap_b32_e32 v156, v158
	ds_read_b128 v[100:103], v195 offset:49280
	ds_read_b128 v[136:139], v195 offset:57472
	ds_read_b64_tr_b16 v[172:173], v185 offset:0
	ds_read_b64_tr_b16 v[174:175], v185 offset:0x800
	ds_read_b64_tr_b16 v[202:203], v185 offset:0x1000
	ds_read_b64_tr_b16 v[204:205], v185 offset:0x1800
	ds_read_b64_tr_b16 v[206:207], v185 offset:0x2000
	ds_read_b64_tr_b16 v[208:209], v185 offset:0x2800
	ds_read_b64_tr_b16 v[224:225], v185 offset:0x3000
	ds_read_b64_tr_b16 v[226:227], v185 offset:0x3800
	s_waitcnt lgkmcnt(9)
	v_mfma_f32_32x32x16_bf16 v[82:97], v[100:103], v[104:107], v[82:97]
	v_permlane32_swap_b32_e32 v157, v159
	v_permlane32_swap_b32_e32 v160, v162
	v_permlane32_swap_b32_e32 v161, v163
	s_waitcnt lgkmcnt(8)
	v_mfma_f32_32x32x16_bf16 v[66:81], v[136:139], v[104:107], v[66:81]
	v_add_u32_e32 v178, s7, v166
	v_add_u32_e32 v100, 1, v178
	v_add_u32_e32 v102, 33, v178
	v_ashrrev_i32_e32 v101, 31, v100
	v_ashrrev_i32_e32 v103, 31, v102
	v_lshlrev_b64 v[140:141], 8, v[100:101]
	v_lshlrev_b64 v[142:143], 8, v[102:103]
	v_lshl_add_u64 v[100:101], v[238:239], 0, v[140:141]
	v_lshl_add_u64 v[140:141], v[234:235], 0, v[140:141]
	v_lshl_add_u64 v[144:145], v[234:235], 0, v[142:143]
	s_nop 0
	s_nop 0
	s_mov_b32 m0, s32
	s_nop 0
	global_load_lds_dwordx4 v[140:141], off
	s_nop 0
	s_add_i32 m0, s32, 0x2000
	s_nop 0
	global_load_lds_dwordx4 v[144:145], off
	s_waitcnt lgkmcnt(0)
; __device__ __forceinline__ void mask_tile(f32x16& p0, f32x16& p1, int dq, unsigned W) {
;     const float NEG = -__builtin_inff();
; #pragma unroll
;     for (int r = 0; r < 16; ++r) {
;         const int c = (r & 3) + 8 * (r >> 2);
;         if ((unsigned)(dq - c) >= W) p0[r] = NEG;
;         if ((unsigned)(dq - c - 32) >= W) p1[r] = NEG;
;     }
; }
; template <int VB>
; __device__ __forceinline__ void pv_tile(f32x16* o, int vb0, bf16x8 pa0, bf16x8 pa1, bf16x8 pa2, bf16x8 pa3) {
;     ...
;     PV_D0(0); PV_D0(1); PV_D0(2); PV_D0(3);
	s_nop 0
	v_mfma_f32_32x32x16_bf16 v[50:65], v[148:151], v[172:175], v[50:65]
	ds_read_b64_tr_b16 v[172:173], v185 offset:0x200
	ds_read_b64_tr_b16 v[174:175], v185 offset:0xa00
	v_mfma_f32_32x32x16_bf16 v[50:65], v[152:155], v[202:205], v[50:65]
	ds_read_b64_tr_b16 v[202:203], v185 offset:0x1200
	ds_read_b64_tr_b16 v[204:205], v185 offset:0x1a00
	v_mfma_f32_32x32x16_bf16 v[50:65], v[156:159], v[206:209], v[50:65]
	ds_read_b64_tr_b16 v[206:207], v185 offset:0x2200
	ds_read_b64_tr_b16 v[208:209], v185 offset:0x2a00
	v_mfma_f32_32x32x16_bf16 v[50:65], v[160:163], v[224:227], v[50:65]
	ds_read_b64_tr_b16 v[224:225], v185 offset:0x3200
	ds_read_b64_tr_b16 v[226:227], v185 offset:0x3a00
	s_waitcnt lgkmcnt(0)
	v_mfma_f32_32x32x16_bf16 v[34:49], v[148:151], v[172:175], v[34:49]
	ds_read_b64_tr_b16 v[172:173], v185 offset:0x400
	ds_read_b64_tr_b16 v[174:175], v185 offset:0xc00
	v_mfma_f32_32x32x16_bf16 v[34:49], v[152:155], v[202:205], v[34:49]
	ds_read_b64_tr_b16 v[202:203], v185 offset:0x1400
	ds_read_b64_tr_b16 v[204:205], v185 offset:0x1c00
	v_mfma_f32_32x32x16_bf16 v[34:49], v[156:159], v[206:209], v[34:49]
	ds_read_b64_tr_b16 v[206:207], v185 offset:0x2400
	ds_read_b64_tr_b16 v[208:209], v185 offset:0x2c00
	v_mfma_f32_32x32x16_bf16 v[34:49], v[160:163], v[224:227], v[34:49]
	ds_read_b64_tr_b16 v[224:225], v185 offset:0x3400
	ds_read_b64_tr_b16 v[226:227], v185 offset:0x3c00
	s_waitcnt lgkmcnt(0)
	v_mfma_f32_32x32x16_bf16 v[18:33], v[148:151], v[172:175], v[18:33]
	ds_read_b64_tr_b16 v[172:173], v185 offset:0x600
	ds_read_b64_tr_b16 v[174:175], v185 offset:0xe00
	v_mfma_f32_32x32x16_bf16 v[18:33], v[152:155], v[202:205], v[18:33]
	ds_read_b64_tr_b16 v[202:203], v185 offset:0x1600
	ds_read_b64_tr_b16 v[204:205], v185 offset:0x1e00
	v_mfma_f32_32x32x16_bf16 v[18:33], v[156:159], v[206:209], v[18:33]
	ds_read_b64_tr_b16 v[206:207], v185 offset:0x2600
	ds_read_b64_tr_b16 v[208:209], v185 offset:0x2e00
	v_mfma_f32_32x32x16_bf16 v[18:33], v[160:163], v[224:227], v[18:33]
	ds_read_b64_tr_b16 v[224:225], v185 offset:0x3600
	ds_read_b64_tr_b16 v[226:227], v185 offset:0x3e00
	s_waitcnt lgkmcnt(0)
	v_mfma_f32_32x32x16_bf16 v[2:17], v[148:151], v[172:175], v[2:17]
	s_cmp_le_i32 s7, s6
	v_mfma_f32_32x32x16_bf16 v[2:17], v[152:155], v[202:205], v[2:17]
	v_mfma_f32_32x32x16_bf16 v[2:17], v[156:159], v[206:209], v[2:17]
	v_mfma_f32_32x32x16_bf16 v[2:17], v[160:163], v[224:227], v[2:17]
	s_cbranch_scc1 .LBB0_91
	v_add_u32_e32 v148, 0x4000007b, v197
	v_cmp_gt_u32_e32 vcc, 2.0, v148
	v_add_u32_e32 v148, 0x5b, v197
	s_nop 0
	v_cndmask_b32_e32 v82, v220, v82, vcc
	v_cmp_lt_u32_e32 vcc, s33, v148
	v_add_u32_e32 v148, 0x7a, v197
	s_nop 0
	v_cndmask_b32_e32 v66, v220, v66, vcc
	v_cmp_lt_u32_e32 vcc, s33, v148
	v_add_u32_e32 v148, 0x5a, v197
	s_nop 0
	v_cndmask_b32_e32 v83, v220, v83, vcc
	v_cmp_lt_u32_e32 vcc, s33, v148
	v_add_u32_e32 v148, 0x79, v197
	s_nop 0
	v_cndmask_b32_e32 v67, v220, v67, vcc
	v_cmp_lt_u32_e32 vcc, s33, v148
	v_add_u32_e32 v148, 0x59, v197
	s_nop 0
	v_cndmask_b32_e32 v84, v220, v84, vcc
	v_cmp_lt_u32_e32 vcc, s33, v148
	v_add_u32_e32 v148, 0x78, v197
	s_nop 0
	v_cndmask_b32_e32 v68, v220, v68, vcc
	v_cmp_lt_u32_e32 vcc, s33, v148
	v_add_u32_e32 v148, 0x58, v197
	s_nop 0
	v_cndmask_b32_e32 v85, v220, v85, vcc
	v_cmp_lt_u32_e32 vcc, s33, v148
	v_add_u32_e32 v148, 0x73, v197
	s_nop 0
	v_cndmask_b32_e32 v69, v220, v69, vcc
	v_cmp_lt_u32_e32 vcc, s33, v148
	v_add_u32_e32 v148, 0x53, v197
	s_nop 0
	v_cndmask_b32_e32 v86, v220, v86, vcc
	v_cmp_lt_u32_e32 vcc, s33, v148
	v_add_u32_e32 v148, 0x72, v197
	s_nop 0
	v_cndmask_b32_e32 v70, v220, v70, vcc
	v_cmp_lt_u32_e32 vcc, s33, v148
	v_add_u32_e32 v148, 0x52, v197
	s_nop 0
	v_cndmask_b32_e32 v87, v220, v87, vcc
	v_cmp_lt_u32_e32 vcc, s33, v148
	v_add_u32_e32 v148, 0x71, v197
	s_nop 0
	v_cndmask_b32_e32 v71, v220, v71, vcc
	v_cmp_lt_u32_e32 vcc, s33, v148
	v_add_u32_e32 v148, 0x51, v197
	s_nop 0
	v_cndmask_b32_e32 v88, v220, v88, vcc
	v_cmp_lt_u32_e32 vcc, s33, v148
	v_add_u32_e32 v148, 0x70, v197
	s_nop 0
	v_cndmask_b32_e32 v72, v220, v72, vcc
	v_cmp_lt_u32_e32 vcc, s33, v148
	v_add_u32_e32 v148, 0x50, v197
	s_nop 0
	v_cndmask_b32_e32 v89, v220, v89, vcc
	v_cmp_lt_u32_e32 vcc, s33, v148
	v_add_u32_e32 v148, 0x6b, v197
	s_nop 0
	v_cndmask_b32_e32 v73, v220, v73, vcc
	v_cmp_lt_u32_e32 vcc, s33, v148
	v_add_u32_e32 v148, 0x4b, v197
	s_nop 0
	v_cndmask_b32_e32 v90, v220, v90, vcc
	v_cmp_lt_u32_e32 vcc, s33, v148
	v_add_u32_e32 v148, 0x6a, v197
	s_nop 0
	v_cndmask_b32_e32 v74, v220, v74, vcc
	v_cmp_lt_u32_e32 vcc, s33, v148
	v_add_u32_e32 v148, 0x4a, v197
	s_nop 0
	v_cndmask_b32_e32 v91, v220, v91, vcc
	v_cmp_lt_u32_e32 vcc, s33, v148
	v_add_u32_e32 v148, 0x69, v197
	s_nop 0
	v_cndmask_b32_e32 v75, v220, v75, vcc
	v_cmp_lt_u32_e32 vcc, s33, v148
	v_add_u32_e32 v148, 0x49, v197
	s_nop 0
	v_cndmask_b32_e32 v92, v220, v92, vcc
	v_cmp_lt_u32_e32 vcc, s33, v148
	v_add_u32_e32 v148, 0x68, v197
	s_nop 0
	v_cndmask_b32_e32 v76, v220, v76, vcc
	v_cmp_lt_u32_e32 vcc, s33, v148
	v_add_u32_e32 v148, 0x48, v197
	s_nop 0
	v_cndmask_b32_e32 v93, v220, v93, vcc
	v_cmp_lt_u32_e32 vcc, s33, v148
	v_add_u32_e32 v148, 0x63, v197
	s_nop 0
	v_cndmask_b32_e32 v77, v220, v77, vcc
	v_cmp_lt_u32_e32 vcc, s33, v148
	v_add_u32_e32 v148, 0x43, v197
	s_nop 0
	v_cndmask_b32_e32 v94, v220, v94, vcc
	v_cmp_lt_u32_e32 vcc, s33, v148
	v_add_u32_e32 v148, 0x62, v197
	s_nop 0
	v_cndmask_b32_e32 v78, v220, v78, vcc
	v_cmp_lt_u32_e32 vcc, s33, v148
	v_add_u32_e32 v148, 0x42, v197
	s_nop 0
	v_cndmask_b32_e32 v95, v220, v95, vcc
	v_cmp_lt_u32_e32 vcc, s33, v148
	v_add_u32_e32 v148, 0x61, v197
	s_nop 0
	v_cndmask_b32_e32 v79, v220, v79, vcc
	v_cmp_lt_u32_e32 vcc, s33, v148
	v_add_u32_e32 v148, 0x41, v197
	s_nop 0
	v_cndmask_b32_e32 v96, v220, v96, vcc
	v_cmp_lt_u32_e32 vcc, s33, v148
	v_add_u32_e32 v148, 0x60, v197
	s_nop 0
	v_cndmask_b32_e32 v80, v220, v80, vcc
	v_cmp_lt_u32_e32 vcc, s33, v148
	v_add_u32_e32 v148, 64, v197
	s_nop 0
	v_cndmask_b32_e32 v97, v220, v97, vcc
	v_cmp_lt_u32_e32 vcc, s33, v148
	s_nop 1
	v_cndmask_b32_e32 v81, v220, v81, vcc

; __device__ __forceinline__ void partialSM(f32x16& p0, f32x16& p1, float& m_reg, float& mn, float& alpha, bool rs) {
;     ...
;     if (__builtin_expect(__all((pmax - m_reg) * SCALE <= THR), 1)) { mn = m_reg; alpha = 1.f; }
;     else { mn = fmaxf(m_reg, pmax); alpha = __builtin_amdgcn_exp2f((m_reg - mn) * C2); m_reg = mn; }
;     const float mnL = rs ? -mn * C2 : -__builtin_inff();
;     for (int r = 0; r < 16; ++r) p0[r] = fmaf(p0[r], C2, mnL); for (int r = 0; r < 16; ++r) p1[r] = fmaf(p1[r], C2, mnL);
;     for (int r = 0; r < 16; ++r) p0[r] = __builtin_amdgcn_exp2f(p0[r]);
; }
.LBB0_95:
	v_cndmask_b32_e64 v179, v148, v198, s[42:43]
	v_mul_f32_e32 v148, 0xbe0293ee, v179
	v_cndmask_b32_e64 v180, v220, v148, s[40:41]
	v_fmamk_f32 v82, v82, 0x3e0293ee, v180
	v_fmamk_f32 v83, v83, 0x3e0293ee, v180
	v_fmamk_f32 v84, v84, 0x3e0293ee, v180
	v_fmamk_f32 v85, v85, 0x3e0293ee, v180
	v_fmamk_f32 v86, v86, 0x3e0293ee, v180
	v_fmamk_f32 v87, v87, 0x3e0293ee, v180
	v_fmamk_f32 v88, v88, 0x3e0293ee, v180
	v_fmamk_f32 v89, v89, 0x3e0293ee, v180
	v_fmamk_f32 v90, v90, 0x3e0293ee, v180
	v_fmamk_f32 v91, v91, 0x3e0293ee, v180
	v_fmamk_f32 v92, v92, 0x3e0293ee, v180
	v_fmamk_f32 v93, v93, 0x3e0293ee, v180
	v_fmamk_f32 v94, v94, 0x3e0293ee, v180
	v_fmamk_f32 v95, v95, 0x3e0293ee, v180
	v_fmamk_f32 v96, v96, 0x3e0293ee, v180
	v_fmamk_f32 v97, v97, 0x3e0293ee, v180
	v_exp_f32_e32 v148, v82
	v_exp_f32_e32 v163, v83
	v_exp_f32_e32 v149, v84
	v_exp_f32_e32 v162, v85
	v_exp_f32_e32 v150, v86
	v_exp_f32_e32 v161, v87
	v_exp_f32_e32 v151, v88
	v_exp_f32_e32 v160, v89
	v_exp_f32_e32 v152, v90
	v_exp_f32_e32 v159, v91
	v_exp_f32_e32 v153, v92
	v_exp_f32_e32 v158, v93
	v_exp_f32_e32 v154, v94
	v_exp_f32_e32 v157, v95
	v_exp_f32_e32 v155, v96
	v_exp_f32_e32 v156, v97
	v_fmamk_f32 v203, v73, 0x3e0293ee, v180
	v_fmamk_f32 v204, v74, 0x3e0293ee, v180
	v_fmamk_f32 v208, v66, 0x3e0293ee, v180
	v_fmamk_f32 v209, v67, 0x3e0293ee, v180
	v_fmamk_f32 v223, v68, 0x3e0293ee, v180
	v_fmamk_f32 v224, v69, 0x3e0293ee, v180
	v_fmamk_f32 v225, v70, 0x3e0293ee, v180
	v_fmamk_f32 v198, v71, 0x3e0293ee, v180
	v_fmamk_f32 v201, v72, 0x3e0293ee, v180
	v_fmamk_f32 v205, v75, 0x3e0293ee, v180
	v_fmamk_f32 v206, v76, 0x3e0293ee, v180
	v_fmamk_f32 v207, v77, 0x3e0293ee, v180
	v_fmamk_f32 v181, v78, 0x3e0293ee, v180
	v_fmamk_f32 v226, v79, 0x3e0293ee, v180
	v_fmamk_f32 v227, v80, 0x3e0293ee, v180
	v_fmac_f32_e32 v180, 0x3e0293ee, v81
	s_waitcnt lgkmcnt(0)
	s_barrier
; __device__ __forceinline__ void finishSM(f32x16& p0, f32x16& p1, float alpha, float& l_reg, bf16x8& pa0, bf16x8& pa1, bf16x8& pa2, bf16x8& pa3) {
;     for (int r = 0; r < 16; ++r) p1[r] = __builtin_amdgcn_exp2f(p1[r]);
;     float ps = 0; for (int r = 0; r < 16; ++r) ps += p0[r]; for (int r = 0; r < 16; ++r) ps += p1[r];
;     { auto rr = __builtin_amdgcn_permlane32_swap(__float_as_uint(ps), __float_as_uint(ps), false, false);
;       ps = __uint_as_float(rr[0]) + __uint_as_float(rr[1]); }
;     l_reg = l_reg * alpha + ps;
;     ...
;     PK4(p0, 0, pa0); PK4(p0, 8, pa1); PK4(p1, 0, pa2); PK4(p1, 8, pa3);
;     ...
; }
; template <int KB>
; __device__ __forceinline__ void qkt(f32x16& p0, f32x16& p1, const char* K_lds, int r32, int hi, const bf16x8* qr) {
;     p0 = f32x16{}; p1 = f32x16{};
;     const char* kb[4];
; #pragma unroll
;     for (int dd = 0; dd < 4; ++dd) kb[dd] = K_lds + KB * SHM_K + KSWZ(r32, (dd * 16 + hi * 8) * 2);
; #pragma unroll
;     for (int d0 = 0; d0 < 8; ++d0) { const char* a = kb[d0 & 3] + (d0 >> 2) * 128;
;         bf16x8 b0 = *reinterpret_cast<const bf16x8*>(a);
;         bf16x8 b1 = *reinterpret_cast<const bf16x8*>(a + 32 * 256);
;         p0 = __builtin_amdgcn_mfma_f32_32x32x16_bf16(b0, qr[d0], p0, 0, 0, 0);
;         p1 = __builtin_amdgcn_mfma_f32_32x32x16_bf16(b1, qr[d0], p1, 0, 0, 0); }
; }
	s_waitcnt vmcnt(0)
	s_lshl_b32 m0, s32, 1
	s_sub_i32 m0, m0, 0x10000
	s_nop 0
	global_load_lds_dwordx4 v[100:101], off
	s_add_i32 m0, m0, 896
	s_nop 0
	global_load_lds_dwordx4 v[100:101], off offset:128
	ds_read_b128 v[66:69], v169 offset:32768
	ds_read_b128 v[70:73], v169 offset:40960
	ds_read_b128 v[172:175], v193 offset:32768
	ds_read_b128 v[228:231], v193 offset:40960
	v_exp_f32_e32 v198, v198
	v_exp_f32_e32 v201, v201
	v_exp_f32_e32 v214, v204
	v_exp_f32_e32 v205, v205
	v_exp_f32_e32 v206, v206
	v_exp_f32_e32 v207, v207
	v_exp_f32_e32 v181, v181
	v_exp_f32_e32 v215, v226
	v_exp_f32_e32 v216, v227
	v_exp_f32_e32 v180, v180
	v_exp_f32_e32 v218, v209
	v_exp_f32_e32 v209, v203
	v_add_f32_e32 v203, 0, v148
	v_add_f32_e32 v203, v163, v203
	v_add_f32_e32 v203, v149, v203
	v_add_f32_e32 v203, v162, v203
	v_add_f32_e32 v203, v150, v203
	v_add_f32_e32 v203, v161, v203
	v_add_f32_e32 v203, v151, v203
	v_add_f32_e32 v203, v160, v203
	s_waitcnt lgkmcnt(3)
	v_mfma_f32_32x32x16_bf16 v[82:97], v[66:69], v[132:135], 0
	v_add_f32_e32 v203, v152, v203
	v_add_f32_e32 v203, v159, v203
	v_add_f32_e32 v203, v153, v203
	v_add_f32_e32 v203, v158, v203
	s_waitcnt lgkmcnt(2)
	v_mfma_f32_32x32x16_bf16 v[66:81], v[70:73], v[132:135], 0
	v_exp_f32_e32 v217, v208
	v_add_f32_e32 v203, v154, v203
	v_add_f32_e32 v203, v157, v203
	v_exp_f32_e32 v219, v223
	s_waitcnt lgkmcnt(1)
	v_mfma_f32_32x32x16_bf16 v[82:97], v[172:175], v[128:131], v[82:97]
	v_add_f32_e32 v203, v155, v203
	v_exp_f32_e32 v222, v224
	v_add_f32_e32 v203, v156, v203
	v_exp_f32_e32 v208, v225
	s_waitcnt lgkmcnt(0)
	v_mfma_f32_32x32x16_bf16 v[66:81], v[228:231], v[128:131], v[66:81]
	v_add_f32_e32 v203, v217, v203
	v_add_f32_e32 v203, v218, v203
	v_add_f32_e32 v203, v219, v203
	v_add_f32_e32 v203, v222, v203
	ds_read_b128 v[172:175], v194 offset:32768
	ds_read_b128 v[228:231], v194 offset:40960
	s_waitcnt lgkmcnt(1)
	v_mfma_f32_32x32x16_bf16 v[82:97], v[172:175], v[124:127], v[82:97]
	v_add_f32_e32 v203, v208, v203
	v_add_f32_e32 v203, v198, v203
	v_add_f32_e32 v203, v201, v203
	v_add_f32_e32 v203, v209, v203
	s_waitcnt lgkmcnt(0)
	v_mfma_f32_32x32x16_bf16 v[66:81], v[228:231], v[124:127], v[66:81]
	v_add_f32_e32 v203, v214, v203
	v_add_f32_e32 v203, v205, v203
	v_add_f32_e32 v203, v206, v203
	v_add_f32_e32 v203, v207, v203
	ds_read_b128 v[172:175], v195 offset:32768
	ds_read_b128 v[228:231], v195 offset:40960
	s_waitcnt lgkmcnt(1)
	v_mfma_f32_32x32x16_bf16 v[82:97], v[172:175], v[120:123], v[82:97]
	v_add_f32_e32 v203, v181, v203
	v_add_f32_e32 v203, v215, v203
	v_add_f32_e32 v203, v216, v203
	v_add_f32_e32 v203, v180, v203
	s_waitcnt lgkmcnt(0)
	v_mfma_f32_32x32x16_bf16 v[66:81], v[228:231], v[120:123], v[66:81]
	v_mov_b32_e32 v204, v203
	v_cvt_pk_bf16_f32 v148, v148, v163
	v_cvt_pk_bf16_f32 v149, v149, v162
	v_cvt_pk_bf16_f32 v150, v150, v161
	ds_read_b128 v[172:175], v169 offset:32896
	ds_read_b128 v[228:231], v169 offset:41088
	s_waitcnt lgkmcnt(1)
	v_mfma_f32_32x32x16_bf16 v[82:97], v[172:175], v[116:119], v[82:97]
	v_cvt_pk_bf16_f32 v151, v151, v160
	v_cvt_pk_bf16_f32 v152, v152, v159
	v_cvt_pk_bf16_f32 v153, v153, v158
	v_cvt_pk_bf16_f32 v154, v154, v157
	s_waitcnt lgkmcnt(0)
	v_mfma_f32_32x32x16_bf16 v[66:81], v[228:231], v[116:119], v[66:81]
	v_cvt_pk_bf16_f32 v155, v155, v156
	v_cvt_pk_bf16_f32 v156, v217, v218
	v_cvt_pk_bf16_f32 v157, v219, v222
	ds_read_b128 v[172:175], v193 offset:32896
	ds_read_b128 v[228:231], v193 offset:41088
	s_waitcnt lgkmcnt(1)
	v_mfma_f32_32x32x16_bf16 v[82:97], v[172:175], v[112:115], v[82:97]
	v_cvt_pk_bf16_f32 v158, v208, v198
	v_cvt_pk_bf16_f32 v159, v201, v209
	v_cvt_pk_bf16_f32 v160, v214, v205
	s_waitcnt lgkmcnt(0)
	v_mfma_f32_32x32x16_bf16 v[66:81], v[228:231], v[112:115], v[66:81]
	v_cvt_pk_bf16_f32 v161, v206, v207
	v_cvt_pk_bf16_f32 v162, v181, v215
	v_cvt_pk_bf16_f32 v163, v216, v180
	ds_read_b128 v[172:175], v194 offset:32896
	ds_read_b128 v[228:231], v194 offset:41088
	s_waitcnt lgkmcnt(1)
	v_mfma_f32_32x32x16_bf16 v[82:97], v[172:175], v[108:111], v[82:97]
	s_nop 1
	v_permlane32_swap_b32_e32 v203, v204
	v_permlane32_swap_b32_e32 v148, v150
	v_permlane32_swap_b32_e32 v149, v151
	s_waitcnt lgkmcnt(0)
	v_mfma_f32_32x32x16_bf16 v[66:81], v[228:231], v[108:111], v[66:81]
	v_permlane32_swap_b32_e32 v152, v154
	v_permlane32_swap_b32_e32 v153, v155
	v_permlane32_swap_b32_e32 v156, v158
	ds_read_b128 v[172:175], v195 offset:32896
	ds_read_b128 v[228:231], v195 offset:41088
	ds_read_b64_tr_b16 v[206:207], v185 offset:0x5000
	ds_read_b64_tr_b16 v[208:209], v185 offset:0x5800
	ds_read_b64_tr_b16 v[224:225], v185 offset:0x6000
	ds_read_b64_tr_b16 v[226:227], v185 offset:0x6800
	s_waitcnt lgkmcnt(5)
	v_mfma_f32_32x32x16_bf16 v[82:97], v[172:175], v[104:107], v[82:97]
	v_permlane32_swap_b32_e32 v157, v159
	v_permlane32_swap_b32_e32 v160, v162
	v_permlane32_swap_b32_e32 v161, v163
	s_waitcnt lgkmcnt(4)
	v_mfma_f32_32x32x16_bf16 v[66:81], v[228:231], v[104:107], v[66:81]
	ds_read_b64_tr_b16 v[172:173], v185 offset:0x4000
	ds_read_b64_tr_b16 v[174:175], v185 offset:0x4800
	ds_read_b64_tr_b16 v[228:229], v185 offset:0x7000
	ds_read_b64_tr_b16 v[230:231], v185 offset:0x7800
	s_cmp_lt_u32 s3, s2
	s_cselect_b64 s[22:23], -1, 0
	s_cmp_ge_u32 s3, s2
	s_cbranch_scc1 .LBB0_97
	v_add_u32_e32 v242, 0x41, v178
	v_add_u32_e32 v246, 0x61, v178
	v_ashrrev_i32_e32 v243, 31, v242
	v_ashrrev_i32_e32 v247, 31, v246
	v_lshlrev_b64 v[140:141], 8, v[242:243]
	v_lshlrev_b64 v[142:143], 8, v[246:247]
	v_lshl_add_u64 v[242:243], v[238:239], 0, v[140:141]
	v_lshl_add_u64 v[140:141], v[234:235], 0, v[140:141]
	v_lshl_add_u64 v[144:145], v[234:235], 0, v[142:143]
	s_nop 0
	s_nop 0
	s_add_i32 m0, s32, 0x4000
	s_nop 0
	global_load_lds_dwordx4 v[140:141], off
	s_nop 0
	s_add_i32 m0, s32, 0x6000
	s_nop 0
	global_load_lds_dwordx4 v[144:145], off
	s_mov_b32 s100, 1

; #define SBAR() __builtin_amdgcn_sched_barrier(0)
; #define SLOAD_H(Kp, Vp, k0) do { S.st_v0 = load8(ROW(Vp, k0, sr)); S.st_v1 = load8(ROW(Vp, k0, 32 + sr));              \
;                          S.st_k0 = load8(ROW(Kp, k0, sr)); S.st_k1 = load8(ROW(Kp, k0, 32 + sr)); } while (0)
; __device__ __forceinline__ void partialSM(f32x16& p0, f32x16& p1, float& m_reg, float& mn, float& alpha, bool rs) {
;     ...
;     else { mn = fmaxf(m_reg, pmax); alpha = __builtin_amdgcn_exp2f((m_reg - mn) * C2); m_reg = mn; }
;     const float mnL = rs ? -mn * C2 : -__builtin_inff();
;     for (int r = 0; r < 16; ++r) p0[r] = fmaf(p0[r], C2, mnL); for (int r = 0; r < 16; ++r) p1[r] = fmaf(p1[r], C2, mnL);
;     for (int r = 0; r < 16; ++r) p0[r] = __builtin_amdgcn_exp2f(p0[r]);
; }
; __device__ __forceinline__ void moba_block(const BlockRef& cur, const BlockRef& nxt, char* lds, Seam& S) {
;     ...
;     const bool even = (NT & 1) == 0;
;     if (even) { SBAR(); qkt<1>(pB0, pB1, K_lds, r32, hi, S.qr); SBAR(); }
;     SLOAD_H(nxt.K, nxt.V, 0); SBAR();
; #pragma unroll
;     for (int d0 = 0; d0 < 8; ++d0) S.qr[d0] = load8(nxt.Q + (size_t)(wid * QBLK + r32) * D + d0 * 16 + hi * 8);
;     SBAR();
;     finishSM(pA0, pA1, alA, l_reg, pa0, pa1, pa2, pa3); SBAR();
;     pv_tile<0>(o, vb0, pa0, pa1, pa2, pa3);
.LBB0_105:
	v_cndmask_b32_e64 v198, v100, v179, s[42:43]
	v_mul_f32_e32 v100, 0xbe0293ee, v198
	v_cndmask_b32_e64 v100, v220, v100, s[40:41]
	v_mov_b32_e32 v101, v100
	v_fmamk_f32 v82, v82, 0x3e0293ee, v100
	v_fmamk_f32 v83, v83, 0x3e0293ee, v100
	v_fmamk_f32 v84, v84, 0x3e0293ee, v100
	v_fmamk_f32 v85, v85, 0x3e0293ee, v100
	v_fmamk_f32 v86, v86, 0x3e0293ee, v100
	v_fmamk_f32 v87, v87, 0x3e0293ee, v100
	v_fmamk_f32 v88, v88, 0x3e0293ee, v100
	v_fmamk_f32 v89, v89, 0x3e0293ee, v100
	v_fmamk_f32 v90, v90, 0x3e0293ee, v100
	v_fmamk_f32 v91, v91, 0x3e0293ee, v100
	v_fmamk_f32 v92, v92, 0x3e0293ee, v100
	v_fmamk_f32 v93, v93, 0x3e0293ee, v100
	v_fmamk_f32 v94, v94, 0x3e0293ee, v100
	v_fmamk_f32 v95, v95, 0x3e0293ee, v100
	v_fmamk_f32 v96, v96, 0x3e0293ee, v100
	v_fmac_f32_e32 v101, 0x3e0293ee, v97
	v_exp_f32_e32 v231, v82
	v_exp_f32_e32 v233, v83
	v_exp_f32_e32 v229, v84
	v_exp_f32_e32 v232, v85
	v_exp_f32_e32 v228, v86
	v_exp_f32_e32 v230, v87
	v_exp_f32_e32 v226, v88
	v_exp_f32_e32 v227, v89
	v_exp_f32_e32 v223, v90
	v_exp_f32_e32 v225, v91
	v_exp_f32_e32 v209, v92
	v_exp_f32_e32 v224, v93
	v_exp_f32_e32 v206, v94
	v_exp_f32_e32 v208, v95
	v_exp_f32_e32 v205, v96
	v_exp_f32_e32 v207, v101
	v_pk_fma_f32 v[178:179], v[66:67], s[20:21], v[100:101] op_sel_hi:[1,0,0]
	v_add_f32_e32 v66, v199, v200
	v_fmac_f32_e32 v66, v196, v189
	v_add_f32_e32 v189, v203, v204
	s_add_i32 s0, s3, 2
	s_add_i32 s1, s3, 1
	s_addk_i32 s7, 0x80
	v_pk_fma_f32 v[162:163], v[68:69], s[20:21], v[100:101] op_sel_hi:[1,0,0]
	v_pk_fma_f32 v[158:159], v[70:71], s[20:21], v[100:101] op_sel_hi:[1,0,0]
	v_pk_fma_f32 v[156:157], v[72:73], s[20:21], v[100:101] op_sel_hi:[1,0,0]
	v_pk_fma_f32 v[152:153], v[74:75], s[20:21], v[100:101] op_sel_hi:[1,0,0]
	v_pk_fma_f32 v[180:181], v[76:77], s[20:21], v[100:101] op_sel_hi:[1,0,0]
	v_pk_fma_f32 v[160:161], v[78:79], s[20:21], v[100:101] op_sel_hi:[1,0,0]
	v_pk_fma_f32 v[154:155], v[80:81], s[20:21], v[100:101] op_sel_hi:[1,0,0]
	v_fmac_f32_e32 v189, v66, v202
	s_cmp_lt_u32 s1, s2
	v_add_u32_e32 v197, 0xffffff80, v197
	s_waitcnt vmcnt(0)
	s_waitcnt lgkmcnt(0)
	s_barrier
	s_cbranch_scc0 .LBB0_107
	s_mov_b32 s3, s0
	v_mov_b32_e32 v196, v201
	s_branch .LBB0_89
.LBB0_107:
	s_cmp_eq_u32 s100, 0
	s_cbranch_scc1 .Lmy_exit_nov
	s_lshl_b32 m0, s32, 1
	s_sub_i32 m0, m0, 0xc000
	s_nop 0
	global_load_lds_dwordx4 v[242:243], off
	s_add_i32 m0, m0, 896
	s_nop 0
	global_load_lds_dwordx4 v[242:243], off offset:128
.Lmy_exit_nov:
	ds_read_b128 v[66:69], v169 offset:49152
	ds_read_b128 v[82:85], v169 offset:49280
	ds_read_b128 v[86:89], v193 offset:49152
	ds_read_b128 v[90:93], v193 offset:49280
	s_waitcnt lgkmcnt(3)
	v_mfma_f32_32x32x16_bf16 v[66:81], v[66:69], v[132:135], 0
	s_waitcnt lgkmcnt(1)
	v_mfma_f32_32x32x16_bf16 v[66:81], v[86:89], v[128:131], v[66:81]
	ds_read_b128 v[86:89], v194 offset:49152
	ds_read_b128 v[94:97], v194 offset:49280
	s_waitcnt lgkmcnt(1)
	v_mfma_f32_32x32x16_bf16 v[66:81], v[86:89], v[124:127], v[66:81]
	ds_read_b128 v[86:89], v195 offset:49152
	ds_read_b128 v[100:103], v195 offset:49280
	s_waitcnt lgkmcnt(1)
	v_mfma_f32_32x32x16_bf16 v[66:81], v[86:89], v[120:123], v[66:81]
	v_mfma_f32_32x32x16_bf16 v[66:81], v[82:85], v[116:119], v[66:81]
	ds_read_b128 v[82:85], v169 offset:57344
	s_waitcnt vmcnt(2)
	ds_read_b128 v[140:143], v169 offset:57472
	ds_read_b128 v[170:173], v193 offset:57344
	ds_read_b128 v[174:177], v193 offset:57472
	ds_read_b128 v[234:237], v194 offset:57344
	ds_read_b128 v[238:241], v194 offset:57472
	ds_read_b128 v[242:245], v195 offset:57344
	ds_read_b128 v[192:195], v195 offset:57472
	v_mfma_f32_32x32x16_bf16 v[66:81], v[90:93], v[112:115], v[66:81]
	v_mfma_f32_32x32x16_bf16 v[66:81], v[94:97], v[108:111], v[66:81]
	s_waitcnt lgkmcnt(8)
	v_mfma_f32_32x32x16_bf16 v[66:81], v[100:103], v[104:107], v[66:81]
	v_lshlrev_b64 v[86:87], 8, v[166:167]
	v_ashrrev_i32_e32 v169, 31, v168
	v_lshl_add_u64 v[88:89], s[16:17], 0, v[86:87]
	v_lshlrev_b64 v[90:91], 8, v[168:169]
	v_lshl_add_u64 v[88:89], v[88:89], 0, v[98:99]
	v_lshl_add_u64 v[92:93], s[16:17], 0, v[90:91]
	v_lshl_add_u64 v[86:87], s[28:29], 0, v[86:87]
	v_lshl_add_u64 v[92:93], v[92:93], 0, v[98:99]
	global_load_dwordx4 v[100:103], v[88:89], off
	global_load_dwordx4 v[136:139], v[92:93], off
	v_lshl_add_u64 v[86:87], v[86:87], 0, v[98:99]
	v_lshl_add_u64 v[88:89], s[28:29], 0, v[90:91]
	v_lshl_add_u64 v[88:89], v[88:89], 0, v[98:99]
	global_load_dwordx4 v[144:147], v[86:87], off
	global_load_dwordx4 v[148:151], v[88:89], off
	s_waitcnt lgkmcnt(7)
	v_mfma_f32_32x32x16_bf16 v[82:97], v[82:85], v[132:135], 0
	v_mov_b32_e32 v165, v99
	s_waitcnt lgkmcnt(5)
	v_mfma_f32_32x32x16_bf16 v[82:97], v[170:173], v[128:131], v[82:97]
	s_waitcnt lgkmcnt(3)
	v_mfma_f32_32x32x16_bf16 v[82:97], v[234:237], v[124:127], v[82:97]
	s_waitcnt lgkmcnt(1)
	v_mfma_f32_32x32x16_bf16 v[82:97], v[242:245], v[120:123], v[82:97]
	v_mfma_f32_32x32x16_bf16 v[82:97], v[140:143], v[116:119], v[82:97]
	v_or_b32_e32 v116, s94, v184
	v_ashrrev_i32_e32 v117, 31, v116
	v_lshlrev_b64 v[116:117], 8, v[116:117]
	v_lshl_add_u64 v[116:117], s[14:15], 0, v[116:117]
	v_lshl_add_u64 v[140:141], v[116:117], 0, v[164:165]
	v_mfma_f32_32x32x16_bf16 v[82:97], v[174:177], v[112:115], v[82:97]
	global_load_dwordx4 v[132:135], v[140:141], off
	global_load_dwordx4 v[128:131], v[140:141], off offset:32
	global_load_dwordx4 v[124:127], v[140:141], off offset:64
	global_load_dwordx4 v[120:123], v[140:141], off offset:96
	global_load_dwordx4 v[116:119], v[140:141], off offset:128
	global_load_dwordx4 v[112:115], v[140:141], off offset:160
	v_mfma_f32_32x32x16_bf16 v[82:97], v[238:241], v[108:111], v[82:97]
	global_load_dwordx4 v[108:111], v[140:141], off offset:192
	s_nop 0
	global_load_dwordx4 v[140:143], v[140:141], off offset:224
	s_waitcnt lgkmcnt(0)
; __device__ __forceinline__ void finishSM(f32x16& p0, f32x16& p1, float alpha, float& l_reg, bf16x8& pa0, bf16x8& pa1, bf16x8& pa2, bf16x8& pa3) {
;     for (int r = 0; r < 16; ++r) p1[r] = __builtin_amdgcn_exp2f(p1[r]);
;     float ps = 0; for (int r = 0; r < 16; ++r) ps += p0[r]; for (int r = 0; r < 16; ++r) ps += p1[r];
;     { auto rr = __builtin_amdgcn_permlane32_swap(__float_as_uint(ps), __float_as_uint(ps), false, false);
;       ps = __uint_as_float(rr[0]) + __uint_as_float(rr[1]); }
;     l_reg = l_reg * alpha + ps;
;     ...
;     PK4(p0, 0, pa0); PK4(p0, 8, pa1); PK4(p1, 0, pa2); PK4(p1, 8, pa3);
;     ...
; }
; template <int KB>
; __device__ __forceinline__ void qkt(f32x16& p0, f32x16& p1, const char* K_lds, int r32, int hi, const bf16x8* qr) {
;     p0 = f32x16{}; p1 = f32x16{};
;     const char* kb[4];
; #pragma unroll
;     for (int dd = 0; dd < 4; ++dd) kb[dd] = K_lds + KB * SHM_K + KSWZ(r32, (dd * 16 + hi * 8) * 2);
; #pragma unroll
;     for (int d0 = 0; d0 < 8; ++d0) { const char* a = kb[d0 & 3] + (d0 >> 2) * 128;
;         bf16x8 b0 = *reinterpret_cast<const bf16x8*>(a);
;         bf16x8 b1 = *reinterpret_cast<const bf16x8*>(a + 32 * 256);
;         p0 = __builtin_amdgcn_mfma_f32_32x32x16_bf16(b0, qr[d0], p0, 0, 0, 0);
;         p1 = __builtin_amdgcn_mfma_f32_32x32x16_bf16(b1, qr[d0], p1, 0, 0, 0); }
; }
; template <int VB>
; __device__ __forceinline__ void pv_tile(f32x16* o, int vb0, bf16x8 pa0, bf16x8 pa1, bf16x8 pa2, bf16x8 pa3) {
;     ...
;     PV_D0(0); PV_D0(1); PV_D0(2); PV_D0(3);
;     ...
; }
	v_mfma_f32_32x32x16_bf16 v[82:97], v[192:195], v[104:107], v[82:97]
	v_add_f32_e32 v98, 0, v231
	v_add_f32_e32 v98, v233, v98
	v_add_f32_e32 v98, v229, v98
	v_add_f32_e32 v98, v232, v98
	v_add_f32_e32 v98, v228, v98
	v_add_f32_e32 v98, v230, v98
	v_add_f32_e32 v98, v226, v98
	v_add_f32_e32 v98, v227, v98
	v_add_f32_e32 v98, v223, v98
	v_add_f32_e32 v98, v225, v98
	v_add_f32_e32 v98, v209, v98
	v_add_f32_e32 v98, v224, v98
	v_exp_f32_e32 v105, v178
	v_add_f32_e32 v98, v206, v98
	v_exp_f32_e32 v106, v179
	v_add_f32_e32 v98, v208, v98
	v_exp_f32_e32 v107, v162
	v_add_f32_e32 v98, v205, v98
	v_exp_f32_e32 v162, v163
	v_add_f32_e32 v98, v207, v98
	v_exp_f32_e32 v163, v158
	v_add_f32_e32 v98, v105, v98
	v_exp_f32_e32 v164, v159
	v_add_f32_e32 v98, v106, v98
	v_exp_f32_e32 v165, v156
	v_add_f32_e32 v98, v107, v98
	v_exp_f32_e32 v166, v157
	v_add_f32_e32 v98, v162, v98
	v_exp_f32_e32 v167, v152
	v_add_f32_e32 v98, v163, v98
	v_exp_f32_e32 v168, v153
	v_add_f32_e32 v98, v164, v98
	v_exp_f32_e32 v169, v180
	v_add_f32_e32 v98, v165, v98
	v_exp_f32_e32 v170, v181
	v_add_f32_e32 v98, v166, v98
	v_exp_f32_e32 v171, v160
	v_add_f32_e32 v98, v167, v98
	v_exp_f32_e32 v172, v161
	v_add_f32_e32 v98, v168, v98
	v_exp_f32_e32 v173, v154
	v_add_f32_e32 v98, v169, v98
	v_exp_f32_e32 v174, v155
	v_add_f32_e32 v98, v170, v98
	v_add_f32_e32 v98, v171, v98
	v_add_f32_e32 v98, v172, v98
	v_add_f32_e32 v98, v173, v98
	v_add_f32_e32 v98, v174, v98
	v_mov_b32_e32 v104, v98
	s_nop 1
	v_permlane32_swap_b32_e32 v98, v104
	v_cvt_pk_bf16_f32 v152, v231, v233
	v_cvt_pk_bf16_f32 v153, v229, v232
	v_cvt_pk_bf16_f32 v154, v228, v230
	v_cvt_pk_bf16_f32 v155, v226, v227
	v_cvt_pk_bf16_f32 v156, v223, v225
	v_cvt_pk_bf16_f32 v157, v209, v224
	v_cvt_pk_bf16_f32 v158, v206, v208
	v_cvt_pk_bf16_f32 v159, v205, v207
	v_cvt_pk_bf16_f32 v160, v105, v106
	v_cvt_pk_bf16_f32 v161, v107, v162
	v_cvt_pk_bf16_f32 v162, v163, v164
	v_cvt_pk_bf16_f32 v163, v165, v166
	v_cvt_pk_bf16_f32 v164, v167, v168
	v_cvt_pk_bf16_f32 v165, v169, v170
	v_cvt_pk_bf16_f32 v166, v171, v172
	v_cvt_pk_bf16_f32 v167, v173, v174
	s_nop 0
	v_permlane32_swap_b32_e32 v152, v154
	v_permlane32_swap_b32_e32 v153, v155
	v_permlane32_swap_b32_e32 v156, v158
	v_permlane32_swap_b32_e32 v157, v159
	v_permlane32_swap_b32_e32 v160, v162
	v_permlane32_swap_b32_e32 v161, v163
	v_permlane32_swap_b32_e32 v164, v166
	v_permlane32_swap_b32_e32 v165, v167
	ds_read_b64_tr_b16 v[168:169], v185 offset:0
	ds_read_b64_tr_b16 v[170:171], v185 offset:0x800
	ds_read_b64_tr_b16 v[172:173], v185 offset:0x1000
	ds_read_b64_tr_b16 v[174:175], v185 offset:0x1800
	ds_read_b64_tr_b16 v[176:177], v185 offset:0x2000
	ds_read_b64_tr_b16 v[178:179], v185 offset:0x2800
	ds_read_b64_tr_b16 v[192:193], v185 offset:0x3000
	ds_read_b64_tr_b16 v[194:195], v185 offset:0x3800
	s_waitcnt lgkmcnt(0)
	s_nop 0
	v_mfma_f32_32x32x16_bf16 v[50:65], v[152:155], v[168:171], v[50:65]
	ds_read_b64_tr_b16 v[168:169], v185 offset:0x200
	ds_read_b64_tr_b16 v[170:171], v185 offset:0xa00
	v_mfma_f32_32x32x16_bf16 v[50:65], v[156:159], v[172:175], v[50:65]
	ds_read_b64_tr_b16 v[172:173], v185 offset:0x1200
	ds_read_b64_tr_b16 v[174:175], v185 offset:0x1a00
	v_mfma_f32_32x32x16_bf16 v[50:65], v[160:163], v[176:179], v[50:65]
	ds_read_b64_tr_b16 v[176:177], v185 offset:0x2200
	ds_read_b64_tr_b16 v[178:179], v185 offset:0x2a00
	v_mfma_f32_32x32x16_bf16 v[50:65], v[164:167], v[192:195], v[50:65]
	ds_read_b64_tr_b16 v[192:193], v185 offset:0x3200
	ds_read_b64_tr_b16 v[194:195], v185 offset:0x3a00
	s_waitcnt lgkmcnt(0)
	v_mfma_f32_32x32x16_bf16 v[34:49], v[152:155], v[168:171], v[34:49]
	ds_read_b64_tr_b16 v[168:169], v185 offset:0x400
	ds_read_b64_tr_b16 v[170:171], v185 offset:0xc00
	v_mfma_f32_32x32x16_bf16 v[34:49], v[156:159], v[172:175], v[34:49]
	ds_read_b64_tr_b16 v[172:173], v185 offset:0x1400
	ds_read_b64_tr_b16 v[174:175], v185 offset:0x1c00
	v_mfma_f32_32x32x16_bf16 v[34:49], v[160:163], v[176:179], v[34:49]
	ds_read_b64_tr_b16 v[176:177], v185 offset:0x2400
	ds_read_b64_tr_b16 v[178:179], v185 offset:0x2c00
	v_mfma_f32_32x32x16_bf16 v[34:49], v[164:167], v[192:195], v[34:49]
	ds_read_b64_tr_b16 v[192:193], v185 offset:0x3400
	ds_read_b64_tr_b16 v[194:195], v185 offset:0x3c00
	s_waitcnt lgkmcnt(0)
	v_mfma_f32_32x32x16_bf16 v[18:33], v[152:155], v[168:171], v[18:33]
	ds_read_b64_tr_b16 v[168:169], v185 offset:0x600
	ds_read_b64_tr_b16 v[170:171], v185 offset:0xe00
	v_mfma_f32_32x32x16_bf16 v[18:33], v[156:159], v[172:175], v[18:33]
	ds_read_b64_tr_b16 v[172:173], v185 offset:0x1600
	ds_read_b64_tr_b16 v[174:175], v185 offset:0x1e00
	v_mfma_f32_32x32x16_bf16 v[18:33], v[160:163], v[176:179], v[18:33]
	ds_read_b64_tr_b16 v[176:177], v185 offset:0x2600
	ds_read_b64_tr_b16 v[178:179], v185 offset:0x2e00
	v_mfma_f32_32x32x16_bf16 v[18:33], v[164:167], v[192:195], v[18:33]
	ds_read_b64_tr_b16 v[192:193], v185 offset:0x3600
	ds_read_b64_tr_b16 v[194:195], v185 offset:0x3e00
	s_waitcnt lgkmcnt(0)
	v_mfma_f32_32x32x16_bf16 v[2:17], v[152:155], v[168:171], v[2:17]
	s_lshl_b32 s0, s44, 8
	s_or_b32 s1, s0, 0xff
	s_cmp_le_i32 s1, s6
	v_mfma_f32_32x32x16_bf16 v[2:17], v[156:159], v[172:175], v[2:17]
	v_mfma_f32_32x32x16_bf16 v[2:17], v[160:163], v[176:179], v[2:17]
	v_mfma_f32_32x32x16_bf16 v[2:17], v[164:167], v[192:195], v[2:17]
	s_cbranch_scc1 .LBB0_109
; __device__ __forceinline__ void mask_tile(f32x16& p0, f32x16& p1, int dq, unsigned W) {
;     const float NEG = -__builtin_inff();
; #pragma unroll
;     for (int r = 0; r < 16; ++r) {
;         const int c = (r & 3) + 8 * (r >> 2);
;         if ((unsigned)(dq - c) >= W) p0[r] = NEG;
;         if ((unsigned)(dq - c - 32) >= W) p1[r] = NEG;
;     }
; }
; __device__ __forceinline__ void partialSM(f32x16& p0, f32x16& p1, float& m_reg, float& mn, float& alpha, bool rs) {
;     float pmax = p0[0]; for (int r = 1; r < 16; ++r) pmax = fmaxf(pmax, p0[r]); for (int r = 0; r < 16; ++r) pmax = fmaxf(pmax, p1[r]);
;     if (!rs) pmax = -__builtin_inff();
;     { auto rr = __builtin_amdgcn_permlane32_swap(__float_as_uint(pmax), __float_as_uint(pmax), false, false);
;       pmax = fmaxf(__uint_as_float(rr[0]), __uint_as_float(rr[1])); }
;     constexpr float C2 = 1.4426950408889634f * SCALE;
;     if (__builtin_expect(__all((pmax - m_reg) * SCALE <= THR), 1)) { mn = m_reg; alpha = 1.f; }
;     else { mn = fmaxf(m_reg, pmax); alpha = __builtin_amdgcn_exp2f((m_reg - mn) * C2); m_reg = mn; }
	s_or_b32 s0, s0, 0xc0
	v_subrev_u32_e32 v105, s0, v190
	v_cmp_gt_u32_e32 vcc, 2.0, v105
	v_add_u32_e32 v106, 0xbfffffe0, v105
	s_nop 0
	v_cndmask_b32_e32 v66, v220, v66, vcc
	v_cmp_lt_u32_e32 vcc, s33, v106
	v_add_u32_e32 v106, 0xbfffffff, v105
	s_nop 0
	v_cndmask_b32_e32 v82, v220, v82, vcc
	v_cmp_lt_u32_e32 vcc, s33, v106
	v_add_u32_e32 v106, 0xbfffffdf, v105
	s_nop 0
	v_cndmask_b32_e32 v67, v220, v67, vcc
	v_cmp_lt_u32_e32 vcc, s33, v106
	v_add_u32_e32 v106, 0xbffffffe, v105
	s_nop 0
	v_cndmask_b32_e32 v83, v220, v83, vcc
	v_cmp_lt_u32_e32 vcc, s33, v106
	v_add_u32_e32 v106, 0xbfffffde, v105
	s_nop 0
	v_cndmask_b32_e32 v68, v220, v68, vcc
	v_cmp_lt_u32_e32 vcc, s33, v106
	v_add_u32_e32 v106, 0xbffffffd, v105
	s_nop 0
	v_cndmask_b32_e32 v84, v220, v84, vcc
	v_cmp_lt_u32_e32 vcc, s33, v106
	v_add_u32_e32 v106, 0xbfffffdd, v105
	s_nop 0
	v_cndmask_b32_e32 v69, v220, v69, vcc
	v_cmp_lt_u32_e32 vcc, s33, v106
	v_add_u32_e32 v106, 0xbffffff8, v105
	s_nop 0
	v_cndmask_b32_e32 v85, v220, v85, vcc
	v_cmp_lt_u32_e32 vcc, s33, v106
	v_add_u32_e32 v106, 0xbfffffd8, v105
	s_nop 0
	v_cndmask_b32_e32 v70, v220, v70, vcc
	v_cmp_lt_u32_e32 vcc, s33, v106
	v_add_u32_e32 v106, 0xbffffff7, v105
	s_nop 0
	v_cndmask_b32_e32 v86, v220, v86, vcc
	v_cmp_lt_u32_e32 vcc, s33, v106
	v_add_u32_e32 v106, 0xbfffffd7, v105
	s_nop 0
	v_cndmask_b32_e32 v71, v220, v71, vcc
	v_cmp_lt_u32_e32 vcc, s33, v106
	v_add_u32_e32 v106, 0xbffffff6, v105
	s_nop 0
	v_cndmask_b32_e32 v87, v220, v87, vcc
	v_cmp_lt_u32_e32 vcc, s33, v106
	v_add_u32_e32 v106, 0xbfffffd6, v105
	s_nop 0
	v_cndmask_b32_e32 v72, v220, v72, vcc
	v_cmp_lt_u32_e32 vcc, s33, v106
	v_add_u32_e32 v106, 0xbffffff5, v105
	s_nop 0
	v_cndmask_b32_e32 v88, v220, v88, vcc
	v_cmp_lt_u32_e32 vcc, s33, v106
	v_add_u32_e32 v106, 0xbfffffd5, v105
	s_nop 0
	v_cndmask_b32_e32 v73, v220, v73, vcc
	v_cmp_lt_u32_e32 vcc, s33, v106
	v_add_u32_e32 v106, 0xbffffff0, v105
	s_nop 0
	v_cndmask_b32_e32 v89, v220, v89, vcc
	v_cmp_lt_u32_e32 vcc, s33, v106
	v_add_u32_e32 v106, 0xbfffffd0, v105
	s_nop 0
	v_cndmask_b32_e32 v74, v220, v74, vcc
	v_cmp_lt_u32_e32 vcc, s33, v106
	v_add_u32_e32 v106, 0xbfffffef, v105
	s_nop 0
	v_cndmask_b32_e32 v90, v220, v90, vcc
	v_cmp_lt_u32_e32 vcc, s33, v106
	v_add_u32_e32 v106, 0xbfffffcf, v105
	s_nop 0
	v_cndmask_b32_e32 v75, v220, v75, vcc
	v_cmp_lt_u32_e32 vcc, s33, v106
	v_add_u32_e32 v106, 0xbfffffee, v105
	s_nop 0
	v_cndmask_b32_e32 v91, v220, v91, vcc
	v_cmp_lt_u32_e32 vcc, s33, v106
	v_add_u32_e32 v106, 0xbfffffce, v105
	s_nop 0
	v_cndmask_b32_e32 v76, v220, v76, vcc
	v_cmp_lt_u32_e32 vcc, s33, v106
	v_add_u32_e32 v106, 0xbfffffed, v105
	s_nop 0
	v_cndmask_b32_e32 v92, v220, v92, vcc
	v_cmp_lt_u32_e32 vcc, s33, v106
	v_add_u32_e32 v106, 0xbfffffcd, v105
	s_nop 0
	v_cndmask_b32_e32 v77, v220, v77, vcc
	v_cmp_lt_u32_e32 vcc, s33, v106
	v_add_u32_e32 v106, 0xbfffffe8, v105
	s_nop 0
	v_cndmask_b32_e32 v93, v220, v93, vcc
	v_cmp_lt_u32_e32 vcc, s33, v106
	v_add_u32_e32 v106, 0xbfffffc8, v105
	s_nop 0
	v_cndmask_b32_e32 v78, v220, v78, vcc
	v_cmp_lt_u32_e32 vcc, s33, v106
	v_add_u32_e32 v106, 0xbfffffe7, v105
	s_nop 0
	v_cndmask_b32_e32 v94, v220, v94, vcc
	v_cmp_lt_u32_e32 vcc, s33, v106
	v_add_u32_e32 v106, 0xbfffffc7, v105
	s_nop 0
	v_cndmask_b32_e32 v79, v220, v79, vcc
	v_cmp_lt_u32_e32 vcc, s33, v106
	v_add_u32_e32 v106, 0xbfffffe6, v105
	s_nop 0
	v_cndmask_b32_e32 v95, v220, v95, vcc
	v_cmp_lt_u32_e32 vcc, s33, v106
	v_add_u32_e32 v106, 0xbfffffc6, v105
	s_nop 0
	v_cndmask_b32_e32 v80, v220, v80, vcc
	v_cmp_lt_u32_e32 vcc, s33, v106
	v_add_u32_e32 v106, 0xbfffffe5, v105
	v_add_u32_e32 v105, 0xbfffffc5, v105
	v_cndmask_b32_e32 v96, v220, v96, vcc
	v_cmp_lt_u32_e32 vcc, s33, v106
	s_nop 1
	v_cndmask_b32_e32 v81, v220, v81, vcc
	v_cmp_lt_u32_e32 vcc, s33, v105
	s_nop 1
	v_cndmask_b32_e32 v97, v220, v97, vcc
.LBB0_109:
	v_max_f32_e32 v105, v67, v67
	v_max_f32_e32 v106, v66, v66
	v_max_f32_e32 v105, v106, v105
	v_max3_f32 v105, v105, v68, v69
	v_max3_f32 v105, v105, v70, v71
	v_max3_f32 v105, v105, v72, v73
	v_max3_f32 v105, v105, v74, v75
	v_max3_f32 v105, v105, v76, v77
	v_max3_f32 v105, v105, v78, v79
	v_max3_f32 v105, v105, v80, v81
	v_max3_f32 v105, v105, v82, v83
	v_max3_f32 v105, v105, v84, v85
	v_max3_f32 v105, v105, v86, v87
	v_max3_f32 v105, v105, v88, v89
	v_max3_f32 v105, v105, v90, v91
	v_max3_f32 v105, v105, v92, v93
	v_max3_f32 v105, v105, v94, v95
	v_max3_f32 v105, v105, v96, v97
	v_mov_b32_e32 v106, v105
	s_nop 1
	v_permlane32_swap_b32_e32 v105, v106
	v_max_f32_e32 v106, v106, v106
	v_max_f32_e32 v105, v105, v105
	v_max_f32_e32 v105, v105, v106
	v_sub_f32_e32 v106, v105, v198
	v_mul_f32_e32 v106, 0x3db504f3, v106
	v_cmp_ge_f32_e32 vcc, s91, v106
	v_max_f32_e32 v106, v198, v198
	v_max_f32_e32 v106, v106, v105
	v_sub_f32_e32 v105, v198, v106
	v_mul_f32_e32 v105, 0x3e0293ee, v105
	v_exp_f32_e32 v105, v105
	s_cmp_eq_u64 vcc, exec
	s_cselect_b64 s[40:41], -1, 0
	v_cndmask_b32_e64 v105, v105, 1.0, s[40:41]
	v_cmp_gt_f32_e32 vcc, 1.0, v105
	s_waitcnt vmcnt(12)
	s_barrier
	s_cbranch_vccz .LBB0_113
	s_and_saveexec_b64 s[0:1], s[38:39]
	ds_write_b32 v187, v105 offset:128
	s_or_b64 exec, exec, s[0:1]
	s_waitcnt lgkmcnt(0)
	ds_read_b128 v[152:155], v186 offset:224
	ds_read_b128 v[156:159], v186 offset:192
	ds_read_b128 v[160:163], v186 offset:160
	ds_read_b128 v[164:167], v186 offset:128
	s_waitcnt lgkmcnt(3)
	v_pk_mul_f32 v[64:65], v[64:65], v[154:155]
	s_waitcnt lgkmcnt(2)
	v_pk_mul_f32 v[60:61], v[60:61], v[158:159]
	s_waitcnt lgkmcnt(1)
	v_pk_mul_f32 v[56:57], v[56:57], v[162:163]
	s_waitcnt lgkmcnt(0)
	v_pk_mul_f32 v[52:53], v[52:53], v[166:167]
	v_pk_mul_f32 v[62:63], v[62:63], v[152:153]
	v_pk_mul_f32 v[58:59], v[58:59], v[156:157]
	v_pk_mul_f32 v[54:55], v[54:55], v[160:161]
	v_pk_mul_f32 v[50:51], v[50:51], v[164:165]
	v_pk_mul_f32 v[48:49], v[48:49], v[154:155]
	v_pk_mul_f32 v[44:45], v[44:45], v[158:159]
	v_pk_mul_f32 v[40:41], v[40:41], v[162:163]
	v_pk_mul_f32 v[36:37], v[36:37], v[166:167]
	v_pk_mul_f32 v[46:47], v[46:47], v[152:153]
	v_pk_mul_f32 v[42:43], v[42:43], v[156:157]
	v_pk_mul_f32 v[38:39], v[38:39], v[160:161]
	v_pk_mul_f32 v[34:35], v[34:35], v[164:165]
	v_pk_mul_f32 v[32:33], v[32:33], v[154:155]
	v_pk_mul_f32 v[28:29], v[28:29], v[158:159]
	v_pk_mul_f32 v[24:25], v[24:25], v[162:163]
	v_pk_mul_f32 v[20:21], v[20:21], v[166:167]
	v_pk_mul_f32 v[30:31], v[30:31], v[152:153]
	v_pk_mul_f32 v[26:27], v[26:27], v[156:157]
	v_pk_mul_f32 v[22:23], v[22:23], v[160:161]
	v_pk_mul_f32 v[18:19], v[18:19], v[164:165]
	v_pk_mul_f32 v[16:17], v[16:17], v[154:155]
	v_pk_mul_f32 v[12:13], v[12:13], v[158:159]
	v_pk_mul_f32 v[8:9], v[8:9], v[162:163]
	v_pk_mul_f32 v[4:5], v[4:5], v[166:167]
	v_pk_mul_f32 v[14:15], v[14:15], v[152:153]
	v_pk_mul_f32 v[10:11], v[10:11], v[156:157]
	v_pk_mul_f32 v[6:7], v[6:7], v[160:161]
	v_pk_mul_f32 v[2:3], v[2:3], v[164:165]
